# attention item table re-dealt with an intermediate skipped-subtile cost (first-skip 0.6, later 0.28 of a full subtile)
# speedup vs baseline: 1.0271x; 1.0018x over previous
.Ltbl:
	s_and_b32 s0, s73, 15
	s_mov_b32 s100, 0x401148b4
	s_cmp_eq_u32 s0, 1
	s_cselect_b32 s100, 0x4004fcbf, s100
	s_cmp_eq_u32 s0, 2
	s_cselect_b32 s100, 0x4025faa4, s100
	s_cmp_eq_u32 s0, 3
	s_cselect_b32 s100, 0x401a077e, s100
	s_cmp_eq_u32 s0, 4
	s_cselect_b32 s100, 0x4030d973, s100
	s_cmp_eq_u32 s0, 5
	s_cselect_b32 s100, 0x401f89af, s100
	s_cmp_eq_u32 s0, 6
	s_cselect_b32 s100, 0x405f07a7, s100
	s_cmp_eq_u32 s0, 7
	s_cselect_b32 s100, 0x4001173d, s100
	s_cmp_eq_u32 s0, 8
	s_cselect_b32 s100, 0x40152c7c, s100
	s_cmp_eq_u32 s0, 9
	s_cselect_b32 s100, 0x400d9eb7, s100
	s_cmp_eq_u32 s0, 10
	s_cselect_b32 s100, 0x404288ed, s100
	s_cmp_eq_u32 s0, 11
	s_cselect_b32 s100, 0x406155b5, s100
	s_cmp_eq_u32 s0, 12
	s_cselect_b32 s100, 0x4020eb2b, s100
	s_cmp_eq_u32 s0, 13
	s_cselect_b32 s100, 0x400a16fb, s100
	s_cmp_eq_u32 s0, 14
	s_cselect_b32 s100, 0x40293a76, s100
	s_cmp_eq_u32 s0, 15
	s_cselect_b32 s100, 0x402dae6e, s100
	s_mov_b32 s74, 0
